# layer-0 out GEMM: gated-residual epilogue with f32 residual pipelined four pieces deep (was one load-wait-store round trip per 32-byte piece)
# speedup vs baseline: 1.0056x; 1.0006x over previous
.Lepi_out_f32:
	v_lshl_add_u32 v152, v168, 11, v166
	v_lshlrev_b32_e32 v148, 2, v152
	v_lshlrev_b32_e32 v152, 1, v152
	s_mov_b64 s[8:9], s[38:39]
	s_mov_b64 s[4:5], s[46:47]
	global_load_dwordx4 v[178:181], v148, s[8:9]
	global_load_dwordx4 v[182:185], v148, s[8:9] offset:16
	global_load_dwordx4 v[186:189], v148, s[8:9] offset:512
	global_load_dwordx4 v[190:193], v148, s[8:9] offset:528
	s_add_u32 s8, s8, 0x20000
	s_addc_u32 s9, s9, 0
	global_load_dwordx4 v[194:197], v148, s[8:9]
	global_load_dwordx4 v[208:211], v148, s[8:9] offset:16
	global_load_dwordx4 v[212:215], v148, s[8:9] offset:512
	global_load_dwordx4 v[216:219], v148, s[8:9] offset:528
	s_add_u32 s8, s8, 0x20000
	s_addc_u32 s9, s9, 0
	s_waitcnt vmcnt(6)
	v_pk_mul_f32 v[144:145], v[144:145], v[66:67]
	v_pk_mul_f32 v[146:147], v[146:147], v[68:69]
	v_pk_mul_f32 v[140:141], v[140:141], v[70:71]
	v_pk_mul_f32 v[142:143], v[142:143], v[72:73]
	v_pk_add_f32 v[144:145], v[144:145], v[178:179]
	v_pk_add_f32 v[146:147], v[146:147], v[180:181]
	v_pk_add_f32 v[140:141], v[140:141], v[182:183]
	v_pk_add_f32 v[142:143], v[142:143], v[184:185]
	v_cvt_pk_bf16_f32 v178, v144, v145
	v_cvt_pk_bf16_f32 v179, v146, v147
	v_cvt_pk_bf16_f32 v180, v140, v141
	v_cvt_pk_bf16_f32 v181, v142, v143
	global_store_dwordx4 v152, v[178:181], s[4:5]
	s_nop 0
	global_load_dwordx4 v[178:181], v148, s[8:9]
	global_load_dwordx4 v[182:185], v148, s[8:9] offset:16
	s_waitcnt vmcnt(7)
	v_pk_mul_f32 v[136:137], v[136:137], v[54:55]
	v_pk_mul_f32 v[138:139], v[138:139], v[56:57]
	v_pk_mul_f32 v[132:133], v[132:133], v[50:51]
	v_pk_mul_f32 v[134:135], v[134:135], v[52:53]
	v_pk_add_f32 v[136:137], v[136:137], v[186:187]
	v_pk_add_f32 v[138:139], v[138:139], v[188:189]
	v_pk_add_f32 v[132:133], v[132:133], v[190:191]
	v_pk_add_f32 v[134:135], v[134:135], v[192:193]
	v_cvt_pk_bf16_f32 v186, v136, v137
	v_cvt_pk_bf16_f32 v187, v138, v139
	v_cvt_pk_bf16_f32 v188, v132, v133
	v_cvt_pk_bf16_f32 v189, v134, v135
	global_store_dwordx4 v152, v[186:189], s[4:5] offset:256
	s_add_u32 s4, s4, 0x10000
	s_addc_u32 s5, s5, 0
	global_load_dwordx4 v[186:189], v148, s[8:9] offset:512
	global_load_dwordx4 v[190:193], v148, s[8:9] offset:528
	s_add_u32 s8, s8, 0x20000
	s_addc_u32 s9, s9, 0
	s_waitcnt vmcnt(8)
	v_pk_mul_f32 v[128:129], v[128:129], v[66:67]
	v_pk_mul_f32 v[130:131], v[130:131], v[68:69]
	v_pk_mul_f32 v[124:125], v[124:125], v[70:71]
	v_pk_mul_f32 v[126:127], v[126:127], v[72:73]
	v_pk_add_f32 v[128:129], v[128:129], v[194:195]
	v_pk_add_f32 v[130:131], v[130:131], v[196:197]
	v_pk_add_f32 v[124:125], v[124:125], v[208:209]
	v_pk_add_f32 v[126:127], v[126:127], v[210:211]
	v_cvt_pk_bf16_f32 v194, v128, v129
	v_cvt_pk_bf16_f32 v195, v130, v131
	v_cvt_pk_bf16_f32 v196, v124, v125
	v_cvt_pk_bf16_f32 v197, v126, v127
	global_store_dwordx4 v152, v[194:197], s[4:5]
	s_nop 0
	global_load_dwordx4 v[194:197], v148, s[8:9]
	global_load_dwordx4 v[208:211], v148, s[8:9] offset:16
	s_waitcnt vmcnt(9)
	v_pk_mul_f32 v[120:121], v[120:121], v[54:55]
	v_pk_mul_f32 v[122:123], v[122:123], v[56:57]
	v_pk_mul_f32 v[116:117], v[116:117], v[50:51]
	v_pk_mul_f32 v[118:119], v[118:119], v[52:53]
	v_pk_add_f32 v[120:121], v[120:121], v[212:213]
	v_pk_add_f32 v[122:123], v[122:123], v[214:215]
	v_pk_add_f32 v[116:117], v[116:117], v[216:217]
	v_pk_add_f32 v[118:119], v[118:119], v[218:219]
	v_cvt_pk_bf16_f32 v212, v120, v121
	v_cvt_pk_bf16_f32 v213, v122, v123
	v_cvt_pk_bf16_f32 v214, v116, v117
	v_cvt_pk_bf16_f32 v215, v118, v119
	global_store_dwordx4 v152, v[212:215], s[4:5] offset:256
	s_add_u32 s4, s4, 0x10000
	s_addc_u32 s5, s5, 0
	global_load_dwordx4 v[212:215], v148, s[8:9] offset:512
	global_load_dwordx4 v[216:219], v148, s[8:9] offset:528
	s_add_u32 s8, s8, 0xa0000
	s_addc_u32 s9, s9, 0
	s_waitcnt vmcnt(9)
	v_pk_mul_f32 v[112:113], v[112:113], v[66:67]
	v_pk_mul_f32 v[114:115], v[114:115], v[68:69]
	v_pk_mul_f32 v[108:109], v[108:109], v[70:71]
	v_pk_mul_f32 v[110:111], v[110:111], v[72:73]
	v_pk_add_f32 v[112:113], v[112:113], v[178:179]
	v_pk_add_f32 v[114:115], v[114:115], v[180:181]
	v_pk_add_f32 v[108:109], v[108:109], v[182:183]
	v_pk_add_f32 v[110:111], v[110:111], v[184:185]
	v_cvt_pk_bf16_f32 v178, v112, v113
	v_cvt_pk_bf16_f32 v179, v114, v115
	v_cvt_pk_bf16_f32 v180, v108, v109
	v_cvt_pk_bf16_f32 v181, v110, v111
	global_store_dwordx4 v152, v[178:181], s[4:5]
	s_nop 0
	global_load_dwordx4 v[178:181], v148, s[8:9]
	global_load_dwordx4 v[182:185], v148, s[8:9] offset:16
	s_waitcnt vmcnt(9)
	v_pk_mul_f32 v[104:105], v[104:105], v[54:55]
	v_pk_mul_f32 v[106:107], v[106:107], v[56:57]
	v_pk_mul_f32 v[100:101], v[100:101], v[50:51]
	v_pk_mul_f32 v[102:103], v[102:103], v[52:53]
	v_pk_add_f32 v[104:105], v[104:105], v[186:187]
	v_pk_add_f32 v[106:107], v[106:107], v[188:189]
	v_pk_add_f32 v[100:101], v[100:101], v[190:191]
	v_pk_add_f32 v[102:103], v[102:103], v[192:193]
	v_cvt_pk_bf16_f32 v186, v104, v105
	v_cvt_pk_bf16_f32 v187, v106, v107
	v_cvt_pk_bf16_f32 v188, v100, v101
	v_cvt_pk_bf16_f32 v189, v102, v103
	global_store_dwordx4 v152, v[186:189], s[4:5] offset:256
	s_add_u32 s4, s4, 0x10000
	s_addc_u32 s5, s5, 0
	global_load_dwordx4 v[186:189], v148, s[8:9] offset:512
	global_load_dwordx4 v[190:193], v148, s[8:9] offset:528
	s_add_u32 s8, s8, 0x20000
	s_addc_u32 s9, s9, 0
	s_waitcnt vmcnt(9)
	v_pk_mul_f32 v[94:95], v[94:95], v[66:67]
	v_pk_mul_f32 v[96:97], v[96:97], v[68:69]
	v_pk_mul_f32 v[90:91], v[90:91], v[70:71]
	v_pk_mul_f32 v[92:93], v[92:93], v[72:73]
	v_pk_add_f32 v[94:95], v[94:95], v[194:195]
	v_pk_add_f32 v[96:97], v[96:97], v[196:197]
	v_pk_add_f32 v[90:91], v[90:91], v[208:209]
	v_pk_add_f32 v[92:93], v[92:93], v[210:211]
	v_cvt_pk_bf16_f32 v194, v94, v95
	v_cvt_pk_bf16_f32 v195, v96, v97
	v_cvt_pk_bf16_f32 v196, v90, v91
	v_cvt_pk_bf16_f32 v197, v92, v93
	global_store_dwordx4 v152, v[194:197], s[4:5]
	s_nop 0
	global_load_dwordx4 v[194:197], v148, s[8:9]
	global_load_dwordx4 v[208:211], v148, s[8:9] offset:16
	s_waitcnt vmcnt(9)
	v_pk_mul_f32 v[86:87], v[86:87], v[54:55]
	v_pk_mul_f32 v[88:89], v[88:89], v[56:57]
	v_pk_mul_f32 v[82:83], v[82:83], v[50:51]
	v_pk_mul_f32 v[84:85], v[84:85], v[52:53]
	v_pk_add_f32 v[86:87], v[86:87], v[212:213]
	v_pk_add_f32 v[88:89], v[88:89], v[214:215]
	v_pk_add_f32 v[82:83], v[82:83], v[216:217]
	v_pk_add_f32 v[84:85], v[84:85], v[218:219]
	v_cvt_pk_bf16_f32 v212, v86, v87
	v_cvt_pk_bf16_f32 v213, v88, v89
	v_cvt_pk_bf16_f32 v214, v82, v83
	v_cvt_pk_bf16_f32 v215, v84, v85
	global_store_dwordx4 v152, v[212:215], s[4:5] offset:256
	s_add_u32 s4, s4, 0x50000
	s_addc_u32 s5, s5, 0
	global_load_dwordx4 v[212:215], v148, s[8:9] offset:512
	global_load_dwordx4 v[216:219], v148, s[8:9] offset:528
	s_add_u32 s8, s8, 0x20000
	s_addc_u32 s9, s9, 0
	s_waitcnt vmcnt(9)
	v_pk_mul_f32 v[78:79], v[78:79], v[66:67]
	v_pk_mul_f32 v[80:81], v[80:81], v[68:69]
	v_pk_mul_f32 v[74:75], v[74:75], v[70:71]
	v_pk_mul_f32 v[76:77], v[76:77], v[72:73]
	v_pk_add_f32 v[78:79], v[78:79], v[178:179]
	v_pk_add_f32 v[80:81], v[80:81], v[180:181]
	v_pk_add_f32 v[74:75], v[74:75], v[182:183]
	v_pk_add_f32 v[76:77], v[76:77], v[184:185]
	v_cvt_pk_bf16_f32 v178, v78, v79
	v_cvt_pk_bf16_f32 v179, v80, v81
	v_cvt_pk_bf16_f32 v180, v74, v75
	v_cvt_pk_bf16_f32 v181, v76, v77
	global_store_dwordx4 v152, v[178:181], s[4:5]
	s_nop 0
	global_load_dwordx4 v[178:181], v148, s[8:9]
	global_load_dwordx4 v[182:185], v148, s[8:9] offset:16
	s_waitcnt vmcnt(9)
	v_pk_mul_f32 v[62:63], v[62:63], v[54:55]
	v_pk_mul_f32 v[64:65], v[64:65], v[56:57]
	v_pk_mul_f32 v[58:59], v[58:59], v[50:51]
	v_pk_mul_f32 v[60:61], v[60:61], v[52:53]
	v_pk_add_f32 v[62:63], v[62:63], v[186:187]
	v_pk_add_f32 v[64:65], v[64:65], v[188:189]
	v_pk_add_f32 v[58:59], v[58:59], v[190:191]
	v_pk_add_f32 v[60:61], v[60:61], v[192:193]
	v_cvt_pk_bf16_f32 v186, v62, v63
	v_cvt_pk_bf16_f32 v187, v64, v65
	v_cvt_pk_bf16_f32 v188, v58, v59
	v_cvt_pk_bf16_f32 v189, v60, v61
	global_store_dwordx4 v152, v[186:189], s[4:5] offset:256
	s_add_u32 s4, s4, 0x10000
	s_addc_u32 s5, s5, 0
	global_load_dwordx4 v[186:189], v148, s[8:9] offset:512
	global_load_dwordx4 v[190:193], v148, s[8:9] offset:528
	s_add_u32 s8, s8, 0x20000
	s_addc_u32 s9, s9, 0
	s_waitcnt vmcnt(9)
	v_pk_mul_f32 v[46:47], v[46:47], v[66:67]
	v_pk_mul_f32 v[48:49], v[48:49], v[68:69]
	v_pk_mul_f32 v[42:43], v[42:43], v[70:71]
	v_pk_mul_f32 v[44:45], v[44:45], v[72:73]
	v_pk_add_f32 v[46:47], v[46:47], v[194:195]
	v_pk_add_f32 v[48:49], v[48:49], v[196:197]
	v_pk_add_f32 v[42:43], v[42:43], v[208:209]
	v_pk_add_f32 v[44:45], v[44:45], v[210:211]
	v_cvt_pk_bf16_f32 v194, v46, v47
	v_cvt_pk_bf16_f32 v195, v48, v49
	v_cvt_pk_bf16_f32 v196, v42, v43
	v_cvt_pk_bf16_f32 v197, v44, v45
	global_store_dwordx4 v152, v[194:197], s[4:5]
	s_nop 0
	global_load_dwordx4 v[194:197], v148, s[8:9]
	global_load_dwordx4 v[208:211], v148, s[8:9] offset:16
	s_waitcnt vmcnt(9)
	v_pk_mul_f32 v[38:39], v[38:39], v[54:55]
	v_pk_mul_f32 v[40:41], v[40:41], v[56:57]
	v_pk_mul_f32 v[34:35], v[34:35], v[50:51]
	v_pk_mul_f32 v[36:37], v[36:37], v[52:53]
	v_pk_add_f32 v[38:39], v[38:39], v[212:213]
	v_pk_add_f32 v[40:41], v[40:41], v[214:215]
	v_pk_add_f32 v[34:35], v[34:35], v[216:217]
	v_pk_add_f32 v[36:37], v[36:37], v[218:219]
	v_cvt_pk_bf16_f32 v212, v38, v39
	v_cvt_pk_bf16_f32 v213, v40, v41
	v_cvt_pk_bf16_f32 v214, v34, v35
	v_cvt_pk_bf16_f32 v215, v36, v37
	global_store_dwordx4 v152, v[212:215], s[4:5] offset:256
	s_add_u32 s4, s4, 0x10000
	s_addc_u32 s5, s5, 0
	global_load_dwordx4 v[212:215], v148, s[8:9] offset:512
	global_load_dwordx4 v[216:219], v148, s[8:9] offset:528
	s_waitcnt vmcnt(9)
	v_pk_mul_f32 v[30:31], v[30:31], v[66:67]
	v_pk_mul_f32 v[32:33], v[32:33], v[68:69]
	v_pk_mul_f32 v[26:27], v[26:27], v[70:71]
	v_pk_mul_f32 v[28:29], v[28:29], v[72:73]
	v_pk_add_f32 v[30:31], v[30:31], v[178:179]
	v_pk_add_f32 v[32:33], v[32:33], v[180:181]
	v_pk_add_f32 v[26:27], v[26:27], v[182:183]
	v_pk_add_f32 v[28:29], v[28:29], v[184:185]
	v_cvt_pk_bf16_f32 v178, v30, v31
	v_cvt_pk_bf16_f32 v179, v32, v33
	v_cvt_pk_bf16_f32 v180, v26, v27
	v_cvt_pk_bf16_f32 v181, v28, v29
	global_store_dwordx4 v152, v[178:181], s[4:5]
	s_nop 0
	s_waitcnt vmcnt(7)
	v_pk_mul_f32 v[22:23], v[22:23], v[54:55]
	v_pk_mul_f32 v[24:25], v[24:25], v[56:57]
	v_pk_mul_f32 v[18:19], v[18:19], v[50:51]
	v_pk_mul_f32 v[20:21], v[20:21], v[52:53]
	v_pk_add_f32 v[22:23], v[22:23], v[186:187]
	v_pk_add_f32 v[24:25], v[24:25], v[188:189]
	v_pk_add_f32 v[18:19], v[18:19], v[190:191]
	v_pk_add_f32 v[20:21], v[20:21], v[192:193]
	v_cvt_pk_bf16_f32 v186, v22, v23
	v_cvt_pk_bf16_f32 v187, v24, v25
	v_cvt_pk_bf16_f32 v188, v18, v19
	v_cvt_pk_bf16_f32 v189, v20, v21
	global_store_dwordx4 v152, v[186:189], s[4:5] offset:256
	s_add_u32 s4, s4, 0x10000
	s_addc_u32 s5, s5, 0
	s_waitcnt vmcnt(5)
	v_pk_mul_f32 v[14:15], v[14:15], v[66:67]
	v_pk_mul_f32 v[16:17], v[16:17], v[68:69]
	v_pk_mul_f32 v[10:11], v[10:11], v[70:71]
	v_pk_mul_f32 v[12:13], v[12:13], v[72:73]
	v_pk_add_f32 v[14:15], v[14:15], v[194:195]
	v_pk_add_f32 v[16:17], v[16:17], v[196:197]
	v_pk_add_f32 v[10:11], v[10:11], v[208:209]
	v_pk_add_f32 v[12:13], v[12:13], v[210:211]
	v_cvt_pk_bf16_f32 v194, v14, v15
	v_cvt_pk_bf16_f32 v195, v16, v17
	v_cvt_pk_bf16_f32 v196, v10, v11
	v_cvt_pk_bf16_f32 v197, v12, v13
	global_store_dwordx4 v152, v[194:197], s[4:5]
	s_nop 0
	s_waitcnt vmcnt(3)
	v_pk_mul_f32 v[6:7], v[6:7], v[54:55]
	v_pk_mul_f32 v[8:9], v[8:9], v[56:57]
	v_pk_mul_f32 v[2:3], v[2:3], v[50:51]
	v_pk_mul_f32 v[4:5], v[4:5], v[52:53]
	v_pk_add_f32 v[6:7], v[6:7], v[212:213]
	v_pk_add_f32 v[8:9], v[8:9], v[214:215]
	v_pk_add_f32 v[2:3], v[2:3], v[216:217]
	v_pk_add_f32 v[4:5], v[4:5], v[218:219]
	v_cvt_pk_bf16_f32 v212, v6, v7
	v_cvt_pk_bf16_f32 v213, v8, v9
	v_cvt_pk_bf16_f32 v214, v2, v3
	v_cvt_pk_bf16_f32 v215, v4, v5
	global_store_dwordx4 v152, v[212:215], s[4:5] offset:256
	s_nop 0
	s_branch .LBB0_820
